# counted LDS wait at QK0 chain head (lgkmcnt 8 then 8) on top of loop-edge edit
# speedup vs baseline: 1.0169x; 1.0031x over previous
.Lfh:
	s_setprio 1
	s_waitcnt lgkmcnt(8)
	v_mfma_f32_32x32x16_bf16 v[64:79], v[168:171], v[80:83], v[238:253]
	ds_read_b128 v[180:183], v237 offset:53248
	ds_read_b128 v[176:179], v237 offset:53280
	v_add_u32_e32 v172, vcc_lo, v229
	v_add_u32_e32 v218, vcc_lo, v233
	v_mfma_f32_32x32x16_bf16 v[64:79], v[160:163], v[84:87], v[64:79]
	ds_read_b128 v[196:199], v237 offset:57856
	ds_read_b128 v[188:191], v237 offset:62464
	v_mfma_f32_32x32x16_bf16 v[64:79], v[164:167], v[88:91], v[64:79]
	ds_read_b128 v[200:203], v217 offset:13824
	ds_read_b128 v[184:187], v217 offset:13856
	v_mfma_f32_32x32x16_bf16 v[64:79], v[152:155], v[92:95], v[64:79]
	ds_read_b128 v[204:207], v237 offset:57888
	ds_read_b128 v[192:195], v237 offset:62496
	s_waitcnt lgkmcnt(8)
	v_mfma_f32_32x32x16_bf16 v[64:79], v[156:159], v[96:99], v[64:79]
	ds_read_b128 v[168:171], v172 offset:8704
	ds_read_b128 v[160:163], v172 offset:8736
	v_mfma_f32_32x32x16_bf16 v[64:79], v[128:131], v[100:103], v[64:79]
	ds_read_b128 v[164:167], v172 offset:8768
	ds_read_b128 v[152:155], v172 offset:8800
	v_mfma_f32_32x32x16_bf16 v[64:79], v[132:135], v[104:107], v[64:79]
	ds_read_b128 v[156:159], v172 offset:8832
	ds_read_b128 v[128:131], v172 offset:8864
	v_mfma_f32_32x32x16_bf16 v[64:79], v[136:139], v[108:111], v[64:79]
	ds_read_b128 v[132:135], v172 offset:8896
	ds_read_b128 v[136:139], v172 offset:8928
	v_mfma_f32_32x32x16_bf16 v[64:79], v[140:143], v[112:115], v[64:79]
	ds_read_b128 v[140:143], v218 offset:22016
	ds_read_b128 v[172:175], v218 offset:22112
	v_mfma_f32_32x32x16_bf16 v[64:79], v[144:147], v[116:119], v[64:79]
	ds_read_b128 v[144:147], v218 offset:22048
	v_mfma_f32_32x32x16_bf16 v[64:79], v[148:151], v[120:123], v[64:79]
	ds_read_b128 v[148:151], v218 offset:22080
	v_mfma_f32_32x32x16_bf16 v[64:79], v[208:211], v[124:127], v[64:79]
	s_setprio 0
	s_barrier
	s_and_b64 vcc, exec, s[68:69]
	s_cbranch_vccnz .Ldmq_end
	s_cmp_ge_u32 s85, 4
	s_cbranch_scc1 .Lxdq_y
	s_and_b32 s99, s34, 1
	s_mul_i32 s98, s99, 0x4800
	s_addk_i32 s98, 0x6800
	s_mulk_i32 s99, 0x6800
	s_add_i32 s99, s99, s44
	s_add_i32 s98, s98, s44
	s_lshl_b32 s94, s34, 18
	s_lshl_b32 s90, s34, 13
	s_lshl_b32 s91, s34, 7
	s_add_i32 m0, s99, 0x0
	v_add_u32_e32 v255, s94, v221
	global_load_lds_dwordx4 v255, s[8:9]
	s_add_i32 m0, s99, 0x1000
	v_add_u32_e32 v255, s94, v222
	global_load_lds_dwordx4 v255, s[8:9]
	s_add_i32 m0, s99, 0x2000
	v_add_u32_e32 v255, s94, v223
	global_load_lds_dwordx4 v255, s[8:9]
	s_add_i32 m0, s99, 0x3000
	v_add_u32_e32 v255, s94, v224
	global_load_lds_dwordx4 v255, s[8:9]
	s_lshl_b32 s92, s34, s95
	s_add_i32 m0, s99, 0x4000
	v_add_u32_e32 v255, s92, v225
	global_load_lds_dwordx4 v255, s[46:47]
	s_add_i32 m0, s99, 0x5000
	v_add_u32_e32 v255, s90, v226
	global_load_lds_dwordx4 v255, s[52:53]
	s_branch .Ldmq_end
